# attention inner loop: back edge rotated out of the compute segment's head (the loop-back barrier becomes the loop head, counter/exit test moved in front of it, exit path gets its own barrier)
# baseline (speedup 1.0000x reference)
; #define AT_LOAD(S, kt, vt) do { const int kt_ = (kt) < nt ? (kt) : nt - 1, vt_ = (vt) < nt ? (vt) : nt - 1; const bf16_t* Kt_ = Kh + (size_t)kt_ * 64 * 96; \
;         rk##S##0 = *(const u32x4*)(Kt_ + kc0 * 8); rk##S##1 = *(const u32x4*)(Kt_ + kc1c * 8); rv##S = *(const u32x4*)(Vh + (size_t)vd * TK + vt_ * 64 + vch * 8); } while (0)
; #define AT_STOREK(S, bb) do { LAS unsigned char* Kn_ = lds + (bb) * AT_KB; *(LAS u32x4*)(Kn_ + kl0) = rk##S##0; if (tid < 256) *(LAS u32x4*)(Kn_ + kl1) = rk##S##1; } while (0)
; #define AT_STOREV(S, bb) do { *(LAS u32x4*)(lds + 2 * AT_KB + (bb) * AT_VB + vl) = rv##S; } while (0)
; #define AT_STEP(sc0, sc1, sn0, sn1, tt, par, LS, SS) do { \
;             AT_LOAD(LS, (tt) + 3, (tt) + 2); \
;             bf16x8 pa_[4]; \
;             qk(sn0, sn1, (par) ^ 1); \
;             softmax_pack(sc0, sc1, pa_); \
;             pv(pa_, (par)); \
;             AT_STOREK(SS, (par)); AT_STOREV(SS, (par) ^ 1); \
;             __syncthreads(); } while (0)
; DI void attn_phase(const bf16_t* Qb, const bf16_t* Kb, const bf16_t* VT, bf16_t* MIX, LAS unsigned char* lds, int G, int bid, int tid, int wave, int lane) {
;     ...
;         AT_LOAD(A, 0, 0); AT_LOAD(B, 1, 1);
;         AT_STOREK(A, 0); AT_STOREV(A, 0); AT_STOREK(B, 1);
;         AT_LOAD(B, 2, 1);
;         __syncthreads();
;         qk(sA0, sA1, 0);
;         __syncthreads();
;     ...
;         int t = 0;
;         for (; t + 2 < nt; t += 2) { AT_STEP(sA0, sA1, sB0, sB1, t, 0, A, B); AT_STEP(sB0, sB1, sA0, sA1, t + 1, 1, B, A); }
.LBB0_453:
	s_or_b64 exec, exec, s[38:39]
	s_add_i32 s31, s30, -1
	s_add_u32 s26, s8, 0x6000
	s_addc_u32 s27, s9, 0
	s_waitcnt vmcnt(2)
	v_lshl_add_u64 v[0:1], v[160:161], 1, s[26:27]
	global_load_dwordx4 v[104:107], v215, s[26:27]
	global_load_dwordx4 v[112:115], v[0:1], off
	global_load_dwordx4 v[96:99], v[198:199], off offset:128
	s_waitcnt lgkmcnt(0)
	s_barrier
	ds_read_b128 v[0:3], v219
	s_waitcnt vmcnt(3)
	ds_read_b128 v[4:7], v219 offset:32
	s_waitcnt lgkmcnt(1)
	v_mfma_f32_32x32x16_bf16 v[48:63], v[0:3], v[128:131], 0
	ds_read_b128 v[0:3], v219 offset:6656
	ds_read_b128 v[8:11], v219 offset:6688
	s_mul_hi_i32 s27, s44, 0x88000
	s_mul_i32 s26, s44, 0x88000
	v_mov_b32_e32 v167, 0
	v_lshl_add_u64 v[200:201], v[164:165], 0, s[26:27]
	s_mov_b32 s38, 4
	v_mov_b32_e32 v16, 0
	s_waitcnt lgkmcnt(2)
	v_mfma_f32_32x32x16_bf16 v[48:63], v[4:7], v[124:127], v[48:63]
	v_mov_b32_e32 v17, v167
	v_mov_b32_e32 v22, v167
	v_mov_b32_e32 v23, v167
	v_mov_b32_e32 v28, v167
	v_mov_b32_e32 v29, v167
	v_mov_b32_e32 v30, v167
	v_mov_b32_e32 v31, v167
	s_waitcnt lgkmcnt(1)
	v_mfma_f32_32x32x16_bf16 v[32:47], v[0:3], v[128:131], 0
	ds_read_b128 v[0:3], v219 offset:64
	ds_read_b128 v[4:7], v219 offset:96
	s_waitcnt lgkmcnt(1)
	v_mfma_f32_32x32x16_bf16 v[48:63], v[0:3], v[120:123], v[48:63]
	ds_read_b128 v[0:3], v219 offset:6720
	v_mfma_f32_32x32x16_bf16 v[32:47], v[8:11], v[124:127], v[32:47]
	ds_read_b128 v[8:11], v219 offset:6752
	ds_read_b128 v[18:21], v219 offset:6784
	ds_read_b128 v[64:67], v219 offset:6816
	ds_read_b128 v[12:15], v219 offset:128
	ds_read_b128 v[24:27], v219 offset:160
	s_waitcnt lgkmcnt(0)
	v_mfma_f32_32x32x16_bf16 v[32:47], v[0:3], v[120:123], v[32:47]
	v_mov_b32_e32 v0, 0
	v_mov_b32_e32 v1, v167
	v_mov_b32_e32 v2, v167
	v_mov_b32_e32 v3, v167
	v_mfma_f32_32x32x16_bf16 v[48:63], v[4:7], v[116:119], v[48:63]
	v_mov_b32_e32 v4, v167
	v_mov_b32_e32 v5, v167
	v_mov_b32_e32 v6, v167
	v_mov_b32_e32 v7, v167
	v_mfma_f32_32x32x16_bf16 v[32:47], v[8:11], v[116:119], v[32:47]
	v_mov_b32_e32 v8, v167
	v_mov_b32_e32 v9, v167
	v_mov_b32_e32 v10, v167
	v_mov_b32_e32 v11, v167
	v_mfma_f32_32x32x16_bf16 v[48:63], v[12:15], v[108:111], v[48:63]
	v_mov_b32_e32 v12, v167
	v_mov_b32_e32 v13, v167
	v_mov_b32_e32 v14, v167
	v_mov_b32_e32 v15, v167
	v_mfma_f32_32x32x16_bf16 v[32:47], v[18:21], v[108:111], v[32:47]
	v_mov_b32_e32 v18, v167
	v_mov_b32_e32 v19, v167
	v_mov_b32_e32 v20, v167
	v_mov_b32_e32 v21, v167
	v_mfma_f32_32x32x16_bf16 v[48:63], v[24:27], v[100:103], v[48:63]
	v_mov_b32_e32 v24, v167
	v_mov_b32_e32 v25, v167
	v_mov_b32_e32 v26, v167
	v_mov_b32_e32 v27, v167
	v_mfma_f32_32x32x16_bf16 v[32:47], v[64:67], v[100:103], v[32:47]
.LBB0_454:
	s_barrier
	ds_read_b128 v[64:67], v219 offset:13312
	ds_read_b128 v[132:135], v219 offset:13344
	s_nop 4
	v_exp_f32_e32 v169, v48
	v_exp_f32_e32 v171, v49
	v_exp_f32_e32 v173, v50
	s_waitcnt lgkmcnt(1)
	v_mfma_f32_32x32x16_bf16 v[80:95], v[64:67], v[128:131], 0
	ds_read_b128 v[64:67], v219 offset:19968
	ds_read_b128 v[136:139], v219 offset:20000
	v_exp_f32_e32 v175, v51
	v_exp_f32_e32 v177, v52
	v_exp_f32_e32 v181, v53
	v_exp_f32_e32 v183, v54
	v_exp_f32_e32 v185, v55
	v_cvt_pk_bf16_f32 v48, v169, v171
	s_waitcnt lgkmcnt(1)
	v_mfma_f32_32x32x16_bf16 v[64:79], v[64:67], v[128:131], 0
	v_cvt_pk_bf16_f32 v49, v173, v175
	v_cvt_pk_bf16_f32 v50, v177, v181
	v_cvt_pk_bf16_f32 v51, v183, v185
	v_exp_f32_e32 v179, v56
	v_exp_f32_e32 v191, v57
	v_exp_f32_e32 v189, v58
	v_exp_f32_e32 v187, v59
	v_mfma_f32_32x32x16_bf16 v[80:95], v[132:135], v[124:127], v[80:95]
	v_exp_f32_e32 v195, v60
	v_exp_f32_e32 v193, v61
	v_exp_f32_e32 v221, v62
	v_exp_f32_e32 v197, v63
	v_cvt_pk_bf16_f32 v60, v179, v191
	v_cvt_pk_bf16_f32 v61, v189, v187
	v_cvt_pk_bf16_f32 v62, v195, v193
	s_waitcnt lgkmcnt(0)
	v_mfma_f32_32x32x16_bf16 v[64:79], v[136:139], v[124:127], v[64:79]
	ds_read_b128 v[132:135], v219 offset:13376
	ds_read_b128 v[136:139], v219 offset:13408
	v_cvt_pk_bf16_f32 v63, v221, v197
	v_exp_f32_e32 v229, v32
	v_exp_f32_e32 v227, v33
	v_exp_f32_e32 v225, v34
	v_exp_f32_e32 v223, v35
	v_exp_f32_e32 v230, v36
	s_waitcnt lgkmcnt(1)
	v_mfma_f32_32x32x16_bf16 v[80:95], v[132:135], v[120:123], v[80:95]
	ds_read_b128 v[132:135], v219 offset:20032
	ds_read_b128 v[140:143], v219 offset:20064
	v_exp_f32_e32 v228, v37
	v_exp_f32_e32 v226, v38
	v_exp_f32_e32 v224, v39
	v_cvt_pk_bf16_f32 v32, v229, v227
	v_cvt_pk_bf16_f32 v33, v225, v223
	v_cvt_pk_bf16_f32 v34, v230, v228
	s_waitcnt lgkmcnt(1)
	v_mfma_f32_32x32x16_bf16 v[64:79], v[132:135], v[120:123], v[64:79]
	v_cvt_pk_bf16_f32 v35, v226, v224
	s_add_i32 s20, s38, -1
	s_min_u32 s39, s20, s31
	v_exp_f32_e32 v222, v40
	v_exp_f32_e32 v233, v41
	v_exp_f32_e32 v232, v42
	v_exp_f32_e32 v231, v43
	v_mfma_f32_32x32x16_bf16 v[80:95], v[136:139], v[116:119], v[80:95]
	ds_read_b128 v[132:135], v219 offset:13440
	ds_read_b128 v[136:139], v219 offset:13472
	s_mul_i32 s20, s39, 0x1800
	s_lshl_b64 s[26:27], s[20:21], 1
	s_add_u32 s26, s8, s26
	s_addc_u32 s27, s9, s27
	v_exp_f32_e32 v235, v44
	v_exp_f32_e32 v234, v45
	s_waitcnt lgkmcnt(2)
	v_mfma_f32_32x32x16_bf16 v[64:79], v[140:143], v[116:119], v[64:79]
	v_exp_f32_e32 v237, v46
	v_exp_f32_e32 v236, v47
	v_cvt_pk_bf16_f32 v44, v222, v233
	v_cvt_pk_bf16_f32 v45, v232, v231
	v_cvt_pk_bf16_f32 v46, v235, v234
	v_cvt_pk_bf16_f32 v47, v237, v236
	s_waitcnt lgkmcnt(1)
	v_mfma_f32_32x32x16_bf16 v[80:95], v[132:135], v[108:111], v[80:95]
	ds_read_b128 v[132:135], v219 offset:20096
	ds_read_b128 v[140:143], v219 offset:20128
	ds_read_b128 v[52:55], v220 offset:26624
	ds_read_b128 v[56:59], v220 offset:26656
	ds_read_b128 v[36:39], v220 offset:26688
	ds_read_b128 v[40:43], v220 offset:26720
	s_waitcnt lgkmcnt(3)
; #define LAS __attribute__((address_space(3)))
; DI unsigned pk2(float lo, float hi) { f32x2 v = {lo, hi}; bf16x2_t b = __builtin_convertvector(v, bf16x2_t); return __builtin_bit_cast(unsigned, b); }
; #define MFMA32(a, b, c) __builtin_amdgcn_mfma_f32_32x32x16_bf16((a), (b), (c), 0, 0, 0)
; #define AT_STOREV(S, bb) do { *(LAS u32x4*)(lds + 2 * AT_KB + (bb) * AT_VB + vl) = rv##S; } while (0)
; DI void attn_phase(const bf16_t* Qb, const bf16_t* Kb, const bf16_t* VT, bf16_t* MIX, LAS unsigned char* lds, int G, int bid, int tid, int wave, int lane) {
;     ...
;         auto softmax_pack = [&](f32x16& s0, f32x16& s1, bf16x8 (&pa)[4]) __attribute__((always_inline)) {
;             float ps0 = 0.f, ps1 = 0.f;
; #pragma unroll
;             for (int r = 0; r < 16; ++r) { s0[r] = __builtin_amdgcn_exp2f(s0[r]); s1[r] = __builtin_amdgcn_exp2f(s1[r]); ps0 += s0[r]; ps1 += s1[r]; }
;             lsum += ps0 + ps1;
;             u32x4 w;
;             w.x = pk2(s0[0], s0[1]); w.y = pk2(s0[2], s0[3]); w.z = pk2(s0[4], s0[5]); w.w = pk2(s0[6], s0[7]); pa[0] = __builtin_bit_cast(bf16x8, w);
;             w.x = pk2(s0[8], s0[9]); w.y = pk2(s0[10], s0[11]); w.z = pk2(s0[12], s0[13]); w.w = pk2(s0[14], s0[15]); pa[1] = __builtin_bit_cast(bf16x8, w);
;             w.x = pk2(s1[0], s1[1]); w.y = pk2(s1[2], s1[3]); w.z = pk2(s1[4], s1[5]); w.w = pk2(s1[6], s1[7]); pa[2] = __builtin_bit_cast(bf16x8, w);
;             w.x = pk2(s1[8], s1[9]); w.y = pk2(s1[10], s1[11]); w.z = pk2(s1[12], s1[13]); w.w = pk2(s1[14], s1[15]); pa[3] = __builtin_bit_cast(bf16x8, w);
;         };
;         auto pv = [&](const bf16x8 (&pa)[4], const int vbuf) __attribute__((always_inline)) {
;             const LAS unsigned char* Vl = lds + 2 * AT_KB + vbuf * AT_VB;
; #pragma unroll
;             for (int kk = 0; kk < 4; ++kk) {
;                 const LAS unsigned char* vp = Vl + r32 * 144 + kk * 32 + hi * 16;
;                 const bf16x8 b0 = *(const LAS bf16x8*)(vp);
;                 const bf16x8 b1 = *(const LAS bf16x8*)(vp + 32 * 144);
;                 o0 = MFMA32(pa[kk], b0, o0); o1 = MFMA32(pa[kk], b1, o1);
;             }
;         };
;         AT_LOAD(A, 0, 0); AT_LOAD(B, 1, 1);
;         AT_STOREK(A, 0); AT_STOREV(A, 0); AT_STOREK(B, 1);
;         AT_LOAD(B, 2, 1);
;         __syncthreads();
;         qk(sA0, sA1, 0);
;         __syncthreads();
	v_mfma_f32_32x32x16_bf16 v[16:31], v[48:51], v[52:55], v[16:31]
	v_add_f32_e32 v241, 0, v169
	v_add_f32_e32 v242, 0, v229
	v_add_f32_e32 v241, v171, v241
	v_add_f32_e32 v242, v227, v242
	ds_read_b128 v[52:55], v220 offset:31232
	v_mfma_f32_32x32x16_bf16 v[64:79], v[132:135], v[108:111], v[64:79]
	ds_read_b128 v[132:135], v220 offset:31264
	s_waitcnt lgkmcnt(1)
	v_mfma_f32_32x32x16_bf16 v[0:15], v[48:51], v[52:55], v[0:15]
	v_add_f32_e32 v241, v173, v241
	v_add_f32_e32 v242, v225, v242
	v_add_f32_e32 v241, v175, v241
	v_add_f32_e32 v242, v223, v242
	ds_read_b128 v[48:51], v220 offset:31328
	v_mfma_f32_32x32x16_bf16 v[16:31], v[60:63], v[56:59], v[16:31]
	v_add_f32_e32 v241, v177, v241
	v_add_f32_e32 v242, v230, v242
	v_add_f32_e32 v241, v181, v241
	v_add_f32_e32 v242, v228, v242
	s_waitcnt lgkmcnt(1)
	v_mfma_f32_32x32x16_bf16 v[0:15], v[60:63], v[132:135], v[0:15]
	v_add_f32_e32 v241, v183, v241
	v_add_f32_e32 v242, v226, v242
	v_add_f32_e32 v241, v185, v241
	v_add_f32_e32 v242, v224, v242
	v_mfma_f32_32x32x16_bf16 v[16:31], v[32:35], v[36:39], v[16:31]
	v_add_f32_e32 v241, v179, v241
	v_add_f32_e32 v242, v222, v242
	v_add_f32_e32 v241, v191, v241
	v_add_f32_e32 v242, v233, v242
	ds_read_b128 v[36:39], v220 offset:31296
	s_waitcnt lgkmcnt(0)
	v_mfma_f32_32x32x16_bf16 v[0:15], v[32:35], v[36:39], v[0:15]
	v_add_f32_e32 v241, v189, v241
	v_add_f32_e32 v242, v232, v242
	v_add_f32_e32 v241, v187, v241
	v_add_f32_e32 v242, v231, v242
	v_lshl_add_u64 v[32:33], v[160:161], 1, s[26:27]
	v_mfma_f32_32x32x16_bf16 v[80:95], v[136:139], v[100:103], v[80:95]
	v_mfma_f32_32x32x16_bf16 v[64:79], v[140:143], v[100:103], v[64:79]
	global_load_dwordx4 v[140:143], v[32:33], off
	global_load_dwordx4 v[136:139], v215, s[26:27]
	global_load_dwordx4 v[132:135], v[200:201], off
	s_waitcnt vmcnt(4)
	ds_write_b128 v216, v[112:115]
	v_mfma_f32_32x32x16_bf16 v[16:31], v[44:47], v[40:43], v[16:31]
	v_add_f32_e32 v241, v195, v241
	v_add_f32_e32 v242, v235, v242
	v_add_f32_e32 v241, v193, v241
	v_add_f32_e32 v242, v234, v242
	v_add_f32_e32 v241, v221, v241
	v_mfma_f32_32x32x16_bf16 v[0:15], v[44:47], v[48:51], v[0:15]
	v_add_f32_e32 v242, v237, v242
	v_add_f32_e32 v241, v197, v241
	v_add_f32_e32 v242, v236, v242
	v_add_f32_e32 v241, v241, v242
	v_add_f32_e32 v167, v167, v241
	s_and_saveexec_b64 s[26:27], s[4:5]
	ds_write_b128 v218, v[104:107]
	s_or_b64 exec, exec, s[26:27]
	s_waitcnt vmcnt(3)
	ds_write_b128 v217, v[96:99] offset:35840
	s_waitcnt lgkmcnt(0)
	s_barrier
; #define LAS __attribute__((address_space(3)))
; DI void attn_phase(const bf16_t* Qb, const bf16_t* Kb, const bf16_t* VT, bf16_t* MIX, LAS unsigned char* lds, int G, int bid, int tid, int wave, int lane) {
;     ...
;         auto qk = [&](f32x16& s0, f32x16& s1, const int kbuf) __attribute__((always_inline)) {
;             const LAS unsigned char* Kl = lds + kbuf * AT_KB;
;             f32x16 z;
; #pragma unroll
;             for (int r = 0; r < 16; ++r) z[r] = 0.f;
; #pragma unroll
;             for (int d0 = 0; d0 < 6; ++d0) {
;                 const bf16x8 a0 = *(const LAS bf16x8*)(Kl + r32 * 208 + d0 * 32 + hi * 16);
;                 const bf16x8 a1 = *(const LAS bf16x8*)(Kl + (32 + r32) * 208 + d0 * 32 + hi * 16);
;                 if (d0 == 0) { s0 = MFMA32(a0, qf[0], z); s1 = MFMA32(a1, qf[0], z); }
;                 else { s0 = MFMA32(a0, qf[d0], s0); s1 = MFMA32(a1, qf[d0], s1); }
;             }
;         };
;         auto softmax_pack = [&](f32x16& s0, f32x16& s1, bf16x8 (&pa)[4]) __attribute__((always_inline)) {
;             float ps0 = 0.f, ps1 = 0.f;
; #pragma unroll
;             for (int r = 0; r < 16; ++r) { s0[r] = __builtin_amdgcn_exp2f(s0[r]); s1[r] = __builtin_amdgcn_exp2f(s1[r]); ps0 += s0[r]; ps1 += s1[r]; }
;             lsum += ps0 + ps1;
;             u32x4 w;
;             w.x = pk2(s0[0], s0[1]); w.y = pk2(s0[2], s0[3]); w.z = pk2(s0[4], s0[5]); w.w = pk2(s0[6], s0[7]); pa[0] = __builtin_bit_cast(bf16x8, w);
;             w.x = pk2(s0[8], s0[9]); w.y = pk2(s0[10], s0[11]); w.z = pk2(s0[12], s0[13]); w.w = pk2(s0[14], s0[15]); pa[1] = __builtin_bit_cast(bf16x8, w);
;             w.x = pk2(s1[0], s1[1]); w.y = pk2(s1[2], s1[3]); w.z = pk2(s1[4], s1[5]); w.w = pk2(s1[6], s1[7]); pa[2] = __builtin_bit_cast(bf16x8, w);
;             w.x = pk2(s1[8], s1[9]); w.y = pk2(s1[10], s1[11]); w.z = pk2(s1[12], s1[13]); w.w = pk2(s1[14], s1[15]); pa[3] = __builtin_bit_cast(bf16x8, w);
;         };
;         auto pv = [&](const bf16x8 (&pa)[4], const int vbuf) __attribute__((always_inline)) {
;             const LAS unsigned char* Vl = lds + 2 * AT_KB + vbuf * AT_VB;
; #pragma unroll
;             for (int kk = 0; kk < 4; ++kk) {
;                 const LAS unsigned char* vp = Vl + r32 * 144 + kk * 32 + hi * 16;
;                 const bf16x8 b0 = *(const LAS bf16x8*)(vp);
;                 const bf16x8 b1 = *(const LAS bf16x8*)(vp + 32 * 144);
	ds_read_b128 v[32:35], v219
	ds_read_b128 v[96:99], v219 offset:32
	ds_read_b128 v[222:225], v219 offset:6656
	ds_read_b128 v[226:229], v219 offset:6688
	ds_read_b128 v[230:233], v219 offset:64
	ds_read_b128 v[234:237], v219 offset:6720
	ds_read_b128 v[244:247], v219 offset:96
	v_exp_f32_e32 v80, v80
	v_exp_f32_e32 v81, v81
	v_exp_f32_e32 v82, v82
	s_waitcnt lgkmcnt(6)
	v_mfma_f32_32x32x16_bf16 v[48:63], v[32:35], v[128:131], 0
	v_exp_f32_e32 v83, v83
	v_exp_f32_e32 v84, v84
	v_exp_f32_e32 v85, v85
	v_exp_f32_e32 v86, v86
	v_exp_f32_e32 v87, v87
	v_exp_f32_e32 v239, v88
	s_waitcnt lgkmcnt(5)
	v_mfma_f32_32x32x16_bf16 v[48:63], v[96:99], v[124:127], v[48:63]
	ds_read_b128 v[96:99], v219 offset:6752
	v_exp_f32_e32 v238, v89
	v_exp_f32_e32 v89, v90
	v_exp_f32_e32 v88, v91
	v_exp_f32_e32 v91, v92
	v_exp_f32_e32 v93, v93
	v_exp_f32_e32 v92, v94
	s_waitcnt lgkmcnt(5)
	v_mfma_f32_32x32x16_bf16 v[32:47], v[222:225], v[128:131], 0
	ds_read_b128 v[222:225], v219 offset:128
	v_exp_f32_e32 v90, v95
	v_cvt_pk_bf16_f32 v202, v239, v238
	v_cvt_pk_bf16_f32 v203, v89, v88
	v_cvt_pk_bf16_f32 v204, v91, v93
	v_cvt_pk_bf16_f32 v205, v92, v90
	v_exp_f32_e32 v95, v64
	v_exp_f32_e32 v94, v65
	s_waitcnt lgkmcnt(5)
	v_mfma_f32_32x32x16_bf16 v[32:47], v[226:229], v[124:127], v[32:47]
	ds_read_b128 v[226:229], v219 offset:6784
	v_exp_f32_e32 v66, v66
	v_exp_f32_e32 v240, v67
	v_exp_f32_e32 v68, v68
	v_exp_f32_e32 v67, v69
	v_exp_f32_e32 v65, v70
	v_exp_f32_e32 v64, v71
	s_waitcnt lgkmcnt(5)
	v_mfma_f32_32x32x16_bf16 v[48:63], v[230:233], v[120:123], v[48:63]
	ds_read_b128 v[230:233], v219 offset:160
	v_exp_f32_e32 v72, v72
	v_exp_f32_e32 v71, v73
	v_exp_f32_e32 v70, v74
	v_exp_f32_e32 v69, v75
	v_exp_f32_e32 v74, v76
	v_exp_f32_e32 v76, v77
	s_waitcnt lgkmcnt(5)
	v_mfma_f32_32x32x16_bf16 v[32:47], v[234:237], v[120:123], v[32:47]
	ds_read_b128 v[104:107], v219 offset:6816
	v_exp_f32_e32 v75, v78
	v_exp_f32_e32 v73, v79
	s_min_u32 s20, s38, s31
	s_mulk_i32 s20, 0x3000
	s_add_u32 s26, s8, s20
	s_addc_u32 s27, s9, 0
	s_waitcnt lgkmcnt(5)
	v_mfma_f32_32x32x16_bf16 v[48:63], v[244:247], v[116:119], v[48:63]
	ds_read_b128 v[112:115], v220 offset:40448
	v_lshl_add_u64 v[78:79], v[160:161], 1, s[26:27]
	s_lshl_b32 s20, s39, 7
	v_lshl_add_u64 v[206:207], v[198:199], 0, s[20:21]
	s_waitcnt lgkmcnt(5)
	v_mfma_f32_32x32x16_bf16 v[32:47], v[96:99], v[116:119], v[32:47]
	s_waitcnt lgkmcnt(4)
	v_mfma_f32_32x32x16_bf16 v[48:63], v[222:225], v[108:111], v[48:63]
	s_waitcnt lgkmcnt(3)
	v_mfma_f32_32x32x16_bf16 v[32:47], v[226:229], v[108:111], v[32:47]
	s_waitcnt lgkmcnt(2)
	v_mfma_f32_32x32x16_bf16 v[48:63], v[230:233], v[100:103], v[48:63]
	v_cvt_pk_bf16_f32 v96, v80, v81
	v_cvt_pk_bf16_f32 v97, v82, v83
	v_cvt_pk_bf16_f32 v98, v84, v85
	v_cvt_pk_bf16_f32 v99, v86, v87
	s_waitcnt lgkmcnt(1)
	v_mfma_f32_32x32x16_bf16 v[32:47], v[104:107], v[100:103], v[32:47]
	ds_read_b128 v[104:107], v220 offset:35840
	s_waitcnt lgkmcnt(0)
	v_mfma_f32_32x32x16_bf16 v[16:31], v[96:99], v[104:107], v[16:31]
	v_add_f32_e32 v241, 0, v80
	v_add_f32_e32 v242, 0, v95
	v_add_f32_e32 v241, v81, v241
	v_add_f32_e32 v242, v94, v242
	ds_read_b128 v[104:107], v220 offset:35872
	v_mfma_f32_32x32x16_bf16 v[0:15], v[96:99], v[112:115], v[0:15]
	v_add_f32_e32 v241, v82, v241
	v_add_f32_e32 v242, v66, v242
	v_add_f32_e32 v241, v83, v241
	v_add_f32_e32 v242, v240, v242
	ds_read_b128 v[96:99], v220 offset:40480
	ds_read_b128 v[112:115], v220 offset:40512
	s_waitcnt lgkmcnt(1)
	v_mfma_f32_32x32x16_bf16 v[0:15], v[202:205], v[96:99], v[0:15]
	v_add_f32_e32 v241, v84, v241
	v_add_f32_e32 v242, v68, v242
	v_add_f32_e32 v241, v85, v241
	v_add_f32_e32 v242, v67, v242
	ds_read_b128 v[96:99], v220 offset:35904
	v_mfma_f32_32x32x16_bf16 v[16:31], v[202:205], v[104:107], v[16:31]
	v_add_f32_e32 v241, v86, v241
	v_add_f32_e32 v242, v65, v242
	v_add_f32_e32 v241, v87, v241
	v_add_f32_e32 v242, v64, v242
	v_cvt_pk_bf16_f32 v104, v95, v94
	v_cvt_pk_bf16_f32 v105, v66, v240
	v_cvt_pk_bf16_f32 v106, v68, v67
	v_cvt_pk_bf16_f32 v107, v65, v64
	v_cvt_pk_bf16_f32 v202, v72, v71
	v_cvt_pk_bf16_f32 v203, v70, v69
	v_cvt_pk_bf16_f32 v204, v74, v76
	s_waitcnt lgkmcnt(0)
	v_mfma_f32_32x32x16_bf16 v[16:31], v[104:107], v[96:99], v[16:31]
	v_add_f32_e32 v241, v239, v241
	v_add_f32_e32 v242, v72, v242
	v_add_f32_e32 v241, v238, v241
	v_add_f32_e32 v242, v71, v242
	ds_read_b128 v[96:99], v220 offset:35936
	v_cvt_pk_bf16_f32 v205, v75, v73
	v_mfma_f32_32x32x16_bf16 v[0:15], v[104:107], v[112:115], v[0:15]
	v_add_f32_e32 v241, v89, v241
	v_add_f32_e32 v242, v70, v242
	v_add_f32_e32 v241, v88, v241
	v_add_f32_e32 v242, v69, v242
	global_load_dwordx4 v[104:107], v215, s[26:27]
	s_waitcnt lgkmcnt(0)
	v_mfma_f32_32x32x16_bf16 v[16:31], v[202:205], v[96:99], v[16:31]
	v_add_f32_e32 v241, v91, v241
	v_add_f32_e32 v242, v74, v242
	v_add_f32_e32 v241, v93, v241
	v_add_f32_e32 v242, v76, v242
	v_add_f32_e32 v241, v92, v241
	global_load_dwordx4 v[112:115], v[78:79], off
	global_load_dwordx4 v[96:99], v[206:207], off
	ds_read_b128 v[206:209], v220 offset:40544
	s_waitcnt vmcnt(5)
	ds_write_b128 v216, v[140:143] offset:13312
	s_waitcnt lgkmcnt(1)
	v_mfma_f32_32x32x16_bf16 v[0:15], v[202:205], v[206:209], v[0:15]
	v_add_f32_e32 v242, v75, v242
	v_add_f32_e32 v241, v90, v241
	v_add_f32_e32 v242, v73, v242
	v_add_f32_e32 v241, v241, v242
	v_add_f32_e32 v167, v167, v241
	s_and_saveexec_b64 s[26:27], s[4:5]
	s_cbranch_execz .LBB0_458
	s_waitcnt vmcnt(4)
	ds_write_b128 v218, v[136:139] offset:13312
.LBB0_458:
	s_or_b64 exec, exec, s[26:27]
	s_add_i32 s20, s38, 2
	s_cmp_lt_u32 s38, s30
	v_lshl_add_u64 v[200:201], v[200:201], 0, s[72:73]
	s_waitcnt vmcnt(3)
	ds_write_b128 v217, v[132:135] offset:26624
	s_waitcnt lgkmcnt(0)
	s_cbranch_scc0 .Lattn_exit_bar
	s_mov_b32 s38, s20
	s_branch .LBB0_454
.Lattn_exit_bar:
	s_barrier
